# v015 + attention near/far loops: next pair's V LDS-DMA issued before the step-top wait (vmcnt(4) instead of vmcnt(0)) for one more pair of loads in flight
# baseline (speedup 1.0000x reference)
; __device__ __forceinline__ void attn_pair_bases(int pi, int r4, int j0, int rowbase, int h, unsigned& ua, unsigned& ub) {
;     int rk, jtA; bool same; pair_decode(pi, r4, j0, rk, jtA, same);
;     const int jtB = jtA + 16;
;     const bool vA = (jtA >= 0) && (jtA < 2048), vB = (jtB >= 0) && (jtB < 2048);
;     const int jA = vA ? jtA : jtB, jB = vB ? jtB : jtA;
;     ua = (unsigned)(((rowbase + 4 * jA + rk) * AW + h * 64) * 2); ub = (unsigned)(((rowbase + 4 * jB + rk) * AW + h * 64) * 2);
; }
; __device__ __forceinline__ void attn_load_k(int pi, int r4, int j0, int rowbase, int h, int klo, __amdgpu_buffer_rsrc_t Kr, bf16x8 (&Kn)[4]) {
;     unsigned ua, ub; attn_pair_bases(pi, r4, j0, rowbase, h, ua, ub);
;     Kn[0] = __builtin_bit_cast(bf16x8, __builtin_amdgcn_raw_buffer_load_b128(Kr, klo, ua, 0)); Kn[1] = __builtin_bit_cast(bf16x8, __builtin_amdgcn_raw_buffer_load_b128(Kr, klo + 64, ua, 0));
;     Kn[2] = __builtin_bit_cast(bf16x8, __builtin_amdgcn_raw_buffer_load_b128(Kr, klo, ub, 0)); Kn[3] = __builtin_bit_cast(bf16x8, __builtin_amdgcn_raw_buffer_load_b128(Kr, klo + 64, ub, 0));
; }
; __device__ __forceinline__ void attn_dma_v(int pi, int r4, int j0, int rowbase, int h, int vlo, __amdgpu_buffer_rsrc_t Vr, LAS unsigned char* vbuf) {
;     unsigned ua, ub; attn_pair_bases(pi, r4, j0, rowbase, h, ua, ub);
;     __builtin_amdgcn_raw_ptr_buffer_load_lds(Vr, (LAS unsigned*)(vbuf), 16, vlo, ua, 0, 0);
;     __builtin_amdgcn_raw_ptr_buffer_load_lds(Vr, (LAS unsigned*)(vbuf + 1024), 16, vlo + 64, ua, 0, 0);
; template <int MODE, int DRY, int QLO, int QHI>
; __device__ __forceinline__ int attn_step(int o, int& par, const AttnCtx& C, const AttnLane& L, f32x4 (&O)[4][4], float (&mrun)[4], float (&lrun)[4], const bf16x8 (&Qf)[4][2], bf16x8 (&Kn)[4]) {
;     ...
;     asm volatile("s_waitcnt vmcnt(0)" ::: "memory");
;     bf16x8 Vf[4];
;     { LAS const unsigned char* vb = C.vl + par * 4096 + (4 * fq + (fr >> 2)) * 64 + (fr & 3) * 8;
; #pragma unroll
;       for (int dt = 0; dt < 4; ++dt) { const s16x4 lo = vtr(vb + (dt >> 1) * 1024 + (dt & 1) * 32), hi = vtr(vb + 2048 + (dt >> 1) * 1024 + (dt & 1) * 32);
;           Vf[dt] = (bf16x8){lo[0], lo[1], lo[2], lo[3], hi[0], hi[1], hi[2], hi[3]}; }
;       asm volatile("" ::: "memory"); }
;     if (DRY != 2) if (on < 27) attn_dma_v(pn, C.r4, C.j0, C.rowbase, C.h, C.vlo, C.Vr, C.vl + (par ^ 1) * 4096);
.LBB0_578:
	s_lshl_b32 s42, s83, 12
	v_add_u32_e32 v114, s42, v187
	v_cndmask_b32_e64 v128, 0, 1, s[4:5]
	v_cmp_ne_u32_e64 s[0:1], 1, v128
	s_andn2_b64 vcc, exec, s[4:5]
	s_cbranch_vccnz .Lmy_nodma_near
	s_cmp_lt_i32 s43, 18
	s_mov_b32 s4, s63
	s_mov_b32 s14, s80
	s_mov_b32 s5, s43
	s_cbranch_scc1 .LBB0_581
	s_sub_i32 s4, s43, 18
	s_mul_i32 s5, s4, 0xab
	s_bfe_u32 s5, s5, 0x70009
	s_add_i32 s14, s82, s5
	s_and_b32 s14, s14, 3
	s_mul_i32 s5, s5, -3
	s_add_i32 s5, s5, s4
	s_or_b32 s4, s14, s78
	s_mov_b32 s14, s81
.LBB0_581:
	s_lshl_b32 s5, s5, 5
	s_xor_b32 s15, s42, 0x1000
	s_add_i32 s5, s5, s14
	s_add_i32 s15, s59, s15
	s_add_i32 s14, s5, 16
	s_cmpk_lt_u32 s5, 0x800
	s_cselect_b32 s42, s5, s14
	s_cmpk_lt_u32 s14, 0x800
	s_cselect_b32 s5, s14, s5
	s_lshl_b32 s14, s42, 2
	s_add_i32 s14, s14, s4
	s_mulk_i32 s14, 0x600
	s_lshl_b32 s5, s5, 2
	s_add_i32 s14, s14, s62
	s_add_i32 s4, s5, s4
	s_lshl_b32 s14, s14, 1
	s_mulk_i32 s4, 0x600
	s_mov_b32 m0, s15
	s_add_i32 s4, s4, s62
	buffer_load_dwordx4 v182, s[8:11], s14 offen lds
	s_add_i32 m0, s15, 0x400
	s_lshl_b32 s4, s4, 1
	buffer_load_dwordx4 v186, s[8:11], s14 offen lds
	s_add_i32 m0, s15, 0x800
	s_nop 0
	buffer_load_dwordx4 v182, s[8:11], s4 offen lds
	s_add_i32 m0, s15, 0xc00
	s_nop 0
	buffer_load_dwordx4 v186, s[8:11], s4 offen lds
	s_waitcnt vmcnt(4)
	s_branch .Lmy_join_near

; #define LAS __attribute__((address_space(3)))
; __device__ __forceinline__ s16x4 vtr(LAS const unsigned char* p) { return __builtin_bit_cast(s16x4, __builtin_amdgcn_ds_read_tr16_b64_v4i16((LAS v4i16_t*)p)); }
; template <int MODE, int DRY, int QLO, int QHI>
; __device__ __forceinline__ int attn_step(int o, int& par, const AttnCtx& C, const AttnLane& L, f32x4 (&O)[4][4], float (&mrun)[4], float (&lrun)[4], const bf16x8 (&Qf)[4][2], bf16x8 (&Kn)[4]) {
;     ...
;     { LAS const unsigned char* vb = C.vl + par * 4096 + (4 * fq + (fr >> 2)) * 64 + (fr & 3) * 8;
; #pragma unroll
;       for (int dt = 0; dt < 4; ++dt) { const s16x4 lo = vtr(vb + (dt >> 1) * 1024 + (dt & 1) * 32), hi = vtr(vb + 2048 + (dt >> 1) * 1024 + (dt & 1) * 32);
;           Vf[dt] = (bf16x8){lo[0], lo[1], lo[2], lo[3], hi[0], hi[1], hi[2], hi[3]}; }
;       asm volatile("" ::: "memory"); }
.Lmy_join_near:
	ds_read_b64_tr_b16 v[124:125], v114
	ds_read_b64_tr_b16 v[120:121], v114 offset:32
	ds_read_b64_tr_b16 v[116:117], v114 offset:1024
	ds_read_b64_tr_b16 v[112:113], v114 offset:1056
	ds_read_b64_tr_b16 v[126:127], v114 offset:2048
	ds_read_b64_tr_b16 v[122:123], v114 offset:2080
	ds_read_b64_tr_b16 v[118:119], v114 offset:3072
	ds_read_b64_tr_b16 v[114:115], v114 offset:3104

; __device__ __forceinline__ void attn_pair_bases(int pi, int r4, int j0, int rowbase, int h, unsigned& ua, unsigned& ub) {
;     int rk, jtA; bool same; pair_decode(pi, r4, j0, rk, jtA, same);
;     const int jtB = jtA + 16;
;     const bool vA = (jtA >= 0) && (jtA < 2048), vB = (jtB >= 0) && (jtB < 2048);
;     const int jA = vA ? jtA : jtB, jB = vB ? jtB : jtA;
;     ua = (unsigned)(((rowbase + 4 * jA + rk) * AW + h * 64) * 2); ub = (unsigned)(((rowbase + 4 * jB + rk) * AW + h * 64) * 2);
; }
; __device__ __forceinline__ void attn_load_k(int pi, int r4, int j0, int rowbase, int h, int klo, __amdgpu_buffer_rsrc_t Kr, bf16x8 (&Kn)[4]) {
;     unsigned ua, ub; attn_pair_bases(pi, r4, j0, rowbase, h, ua, ub);
;     Kn[0] = __builtin_bit_cast(bf16x8, __builtin_amdgcn_raw_buffer_load_b128(Kr, klo, ua, 0)); Kn[1] = __builtin_bit_cast(bf16x8, __builtin_amdgcn_raw_buffer_load_b128(Kr, klo + 64, ua, 0));
;     Kn[2] = __builtin_bit_cast(bf16x8, __builtin_amdgcn_raw_buffer_load_b128(Kr, klo, ub, 0)); Kn[3] = __builtin_bit_cast(bf16x8, __builtin_amdgcn_raw_buffer_load_b128(Kr, klo + 64, ub, 0));
; }
; __device__ __forceinline__ void attn_dma_v(int pi, int r4, int j0, int rowbase, int h, int vlo, __amdgpu_buffer_rsrc_t Vr, LAS unsigned char* vbuf) {
;     unsigned ua, ub; attn_pair_bases(pi, r4, j0, rowbase, h, ua, ub);
;     __builtin_amdgcn_raw_ptr_buffer_load_lds(Vr, (LAS unsigned*)(vbuf), 16, vlo, ua, 0, 0);
;     __builtin_amdgcn_raw_ptr_buffer_load_lds(Vr, (LAS unsigned*)(vbuf + 1024), 16, vlo + 64, ua, 0, 0);
; template <int MODE, int DRY, int QLO, int QHI>
; __device__ __forceinline__ int attn_step(int o, int& par, const AttnCtx& C, const AttnLane& L, f32x4 (&O)[4][4], float (&mrun)[4], float (&lrun)[4], const bf16x8 (&Qf)[4][2], bf16x8 (&Kn)[4]) {
;     ...
;     asm volatile("s_waitcnt vmcnt(0)" ::: "memory");
;     bf16x8 Vf[4];
;     { LAS const unsigned char* vb = C.vl + par * 4096 + (4 * fq + (fr >> 2)) * 64 + (fr & 3) * 8;
; #pragma unroll
;       for (int dt = 0; dt < 4; ++dt) { const s16x4 lo = vtr(vb + (dt >> 1) * 1024 + (dt & 1) * 32), hi = vtr(vb + 2048 + (dt >> 1) * 1024 + (dt & 1) * 32);
;           Vf[dt] = (bf16x8){lo[0], lo[1], lo[2], lo[3], hi[0], hi[1], hi[2], hi[3]}; }
;       asm volatile("" ::: "memory"); }
;     if (DRY != 2) if (on < 27) attn_dma_v(pn, C.r4, C.j0, C.rowbase, C.h, C.vlo, C.Vr, C.vl + (par ^ 1) * 4096);
.LBB0_625:
	s_lshl_b32 s43, s83, 12
	v_add_u32_e32 v114, s43, v187
	v_cndmask_b32_e64 v128, 0, 1, s[4:5]
	v_cmp_ne_u32_e64 s[0:1], 1, v128
	s_andn2_b64 vcc, exec, s[4:5]
	s_cbranch_vccnz .Lmy_nodma_far
	s_cmp_lt_u32 s42, 18
	s_mov_b32 s4, s63
	s_mov_b32 s14, s80
	s_mov_b32 s5, s42
	s_cbranch_scc1 .LBB0_628
	s_sub_i32 s4, s42, 18
	s_mul_i32 s5, s4, 0xab
	s_bfe_u32 s5, s5, 0x70009
	s_add_i32 s14, s82, s5
	s_and_b32 s14, s14, 3
	s_mul_i32 s5, s5, -3
	s_add_i32 s5, s5, s4
	s_or_b32 s4, s14, s78
	s_mov_b32 s14, s81
.LBB0_628:
	s_lshl_b32 s5, s5, 5
	s_xor_b32 s15, s43, 0x1000
	s_add_i32 s5, s5, s14
	s_add_i32 s15, s59, s15
	s_add_i32 s14, s5, 16
	s_cmpk_lt_u32 s5, 0x800
	s_cselect_b32 s43, s5, s14
	s_cmpk_lt_u32 s14, 0x800
	s_cselect_b32 s5, s14, s5
	s_lshl_b32 s14, s43, 2
	s_add_i32 s14, s14, s4
	s_mulk_i32 s14, 0x600
	s_lshl_b32 s5, s5, 2
	s_add_i32 s14, s14, s62
	s_add_i32 s4, s5, s4
	s_lshl_b32 s14, s14, 1
	s_mulk_i32 s4, 0x600
	s_mov_b32 m0, s15
	s_add_i32 s4, s4, s62
	buffer_load_dwordx4 v182, s[8:11], s14 offen lds
	s_add_i32 m0, s15, 0x400
	s_lshl_b32 s4, s4, 1
	buffer_load_dwordx4 v186, s[8:11], s14 offen lds
	s_add_i32 m0, s15, 0x800
	s_nop 0
	buffer_load_dwordx4 v182, s[8:11], s4 offen lds
	s_add_i32 m0, s15, 0xc00
	s_nop 0
	buffer_load_dwordx4 v186, s[8:11], s4 offen lds
	s_waitcnt vmcnt(4)
	s_branch .Lmy_join_far
